# P4-P5 grid barrier replaced by a per-row-panel barrier: attention-combine rows dealt to the 8 workgroups that consume the panel, same-XCD check with fenced fallback
# speedup vs baseline: 1.0397x; 1.0072x over previous
.LBB0_562:
	v_and_b32_e32 v4, 0x7ff, v1
	v_ashrrev_i32_e32 v3, 11, v1
	v_or_b32_e32 v26, 0x1000, v4
	v_add_u32_e32 v8, 2, v3
	v_add_u32_e32 v10, 4, v3
	v_add_u32_e32 v12, 6, v3
	v_add_u32_e32 v14, 8, v3
	v_add_u32_e32 v16, 10, v3
	v_add_u32_e32 v18, 12, v3
	v_add_u32_e32 v20, 14, v3
	v_lshlrev_b32_e32 v4, 2, v26
	v_mul_hi_i32_i24_e32 v7, 0x6000, v3
	v_mul_i32_i24_e32 v6, 0x6000, v3
	v_mul_hi_i32_i24_e32 v9, 0x6000, v8
	v_mul_i32_i24_e32 v8, 0x6000, v8
	v_mul_hi_i32_i24_e32 v11, 0x6000, v10
	v_mul_i32_i24_e32 v10, 0x6000, v10
	v_mul_hi_i32_i24_e32 v13, 0x6000, v12
	v_mul_i32_i24_e32 v12, 0x6000, v12
	v_mul_hi_i32_i24_e32 v15, 0x6000, v14
	v_mul_i32_i24_e32 v14, 0x6000, v14
	v_mul_hi_i32_i24_e32 v17, 0x6000, v16
	v_mul_i32_i24_e32 v16, 0x6000, v16
	v_mul_hi_i32_i24_e32 v19, 0x6000, v18
	v_mul_i32_i24_e32 v18, 0x6000, v18
	v_mul_hi_i32_i24_e32 v21, 0x6000, v20
	v_mul_i32_i24_e32 v20, 0x6000, v20
	v_lshl_add_u64 v[22:23], s[10:11], 0, v[4:5]
	v_lshl_add_u64 v[24:25], s[12:13], 0, v[4:5]
	v_lshl_add_u64 v[6:7], v[24:25], 0, v[6:7]
	v_lshl_add_u64 v[8:9], v[24:25], 0, v[8:9]
	v_lshl_add_u64 v[10:11], v[24:25], 0, v[10:11]
	v_lshl_add_u64 v[12:13], v[24:25], 0, v[12:13]
	v_lshl_add_u64 v[14:15], v[24:25], 0, v[14:15]
	v_lshl_add_u64 v[16:17], v[24:25], 0, v[16:17]
	v_lshl_add_u64 v[18:19], v[24:25], 0, v[18:19]
	v_lshl_add_u64 v[20:21], v[24:25], 0, v[20:21]
	flat_load_dword v4, v[22:23]
	flat_load_dword v24, v[6:7]
	flat_load_dword v25, v[8:9]
	flat_load_dword v27, v[10:11]
	flat_load_dword v28, v[12:13]
	flat_load_dword v29, v[14:15]
	flat_load_dword v30, v[16:17]
	flat_load_dword v31, v[18:19]
	flat_load_dword v32, v[20:21]
	v_mad_i32_i24 v6, v3, s19, v26
	v_add_u32_e32 v1, s18, v1
	v_cmp_lt_i32_e32 vcc, s20, v1
	v_ashrrev_i32_e32 v7, 31, v6
	s_or_b64 s[16:17], vcc, s[16:17]
	v_lshl_add_u64 v[6:7], v[6:7], 2, s[14:15]
	s_waitcnt vmcnt(0) lgkmcnt(0)
	v_add_f32_e32 v3, v4, v24
	v_add_f32_e32 v3, v3, v25
	v_add_f32_e32 v3, v3, v27
	v_add_f32_e32 v3, v3, v28
	v_add_f32_e32 v3, v3, v29
	v_add_f32_e32 v3, v3, v30
	v_add_f32_e32 v3, v3, v31
	v_add_f32_e32 v3, v3, v32
	flat_store_dword v[6:7], v3 sc1
	s_andn2_b64 exec, exec, s[16:17]
	s_cbranch_execnz .LBB0_562
.LBB0_563:
	s_or_b64 exec, exec, s[8:9]
	s_cmp_gt_u32 s2, 7
	s_cbranch_scc1 .Lg_skip
	s_waitcnt vmcnt(0) lgkmcnt(0)
	s_barrier
	v_cmp_eq_u32_e64 s[62:63], 0, v0
	s_and_saveexec_b64 s[64:65], s[62:63]
	s_cbranch_execz .Lg_rest
	v_mov_b32_e32 v79, 0x7600
	v_mov_b32_e32 v80, 1
	global_atomic_add v79, v80, s[24:25]
.Lg_rest:
	s_or_b64 exec, exec, s[64:65]
.Lg_skip:
	s_cmp_lg_u32 s28, 0
	s_cbranch_scc1 .Lxpre_skip_b
	s_load_dwordx2 s[90:91], s[0:1], 0x0
	s_and_b32 s80, s2, 7
	s_lshl_b32 s80, s80, 2
	s_bfe_u32 s81, s2, 0x20003
	s_add_i32 s80, s80, s81
	s_lshr_b32 s81, s2, 5
	s_lshl_b32 s80, s80, 21
	s_lshl_b32 s81, s81, 10
	s_add_u32 s80, s80, s81
	s_lshr_b32 s82, s28, 2
	s_lshl_b32 s82, s82, 19
	s_add_u32 s80, s80, s82
	s_and_b32 s82, s28, 3
	s_lshl_b32 s82, s82, 7
	s_add_u32 s80, s80, s82
	v_and_b32_e32 v202, 15, v0
	v_lshlrev_b32_e32 v202, 13, v202
	v_bfe_u32 v203, v0, 4, 2
	v_lshl_or_b32 v202, v203, 5, v202
	s_waitcnt lgkmcnt(0)
	s_add_u32 s90, s90, s80
	s_addc_u32 s91, s91, 0
	global_load_dwordx4 v[126:129], v202, s[90:91] nt
	global_load_dwordx4 v[122:125], v202, s[90:91] offset:16 nt
	global_load_dwordx4 v[118:121], v202, s[90:91] offset:512 nt
	global_load_dwordx4 v[114:117], v202, s[90:91] offset:528 nt
	s_add_u32 s90, s90, 0x20000
	s_addc_u32 s91, s91, 0
	global_load_dwordx4 v[110:113], v202, s[90:91] nt
	global_load_dwordx4 v[106:109], v202, s[90:91] offset:16 nt
	global_load_dwordx4 v[102:105], v202, s[90:91] offset:512 nt
	global_load_dwordx4 v[98:101], v202, s[90:91] offset:528 nt
	s_add_u32 s90, s90, 0x20000
	s_addc_u32 s91, s91, 0
	global_load_dwordx4 v[94:97], v202, s[90:91] nt
	global_load_dwordx4 v[90:93], v202, s[90:91] offset:16 nt
	global_load_dwordx4 v[86:89], v202, s[90:91] offset:512 nt
	global_load_dwordx4 v[154:157], v202, s[90:91] offset:528 nt
	s_add_u32 s90, s90, 0x20000
	s_addc_u32 s91, s91, 0
	global_load_dwordx4 v[82:85], v202, s[90:91] nt
	global_load_dwordx4 v[158:161], v202, s[90:91] offset:16 nt
	global_load_dwordx4 v[162:165], v202, s[90:91] offset:512 nt
	global_load_dwordx4 v[166:169], v202, s[90:91] offset:528 nt
	s_add_u32 s90, s90, 0xa0000
	s_addc_u32 s91, s91, 0
	global_load_dwordx4 v[170:173], v202, s[90:91] nt
	global_load_dwordx4 v[174:177], v202, s[90:91] offset:16 nt
	global_load_dwordx4 v[178:181], v202, s[90:91] offset:512 nt
	global_load_dwordx4 v[182:185], v202, s[90:91] offset:528 nt
	s_add_u32 s90, s90, 0x20000
	s_addc_u32 s91, s91, 0
	global_load_dwordx4 v[186:189], v202, s[90:91] nt
	global_load_dwordx4 v[190:193], v202, s[90:91] offset:16 nt
	global_load_dwordx4 v[194:197], v202, s[90:91] offset:512 nt
	global_load_dwordx4 v[198:201], v202, s[90:91] offset:528 nt
	s_add_u32 s90, s90, 0x20000
	s_addc_u32 s91, s91, 0
	global_load_dwordx4 v[206:209], v202, s[90:91] nt
	global_load_dwordx4 v[210:213], v202, s[90:91] offset:16 nt
	global_load_dwordx4 v[214:217], v202, s[90:91] offset:512 nt
	global_load_dwordx4 v[218:221], v202, s[90:91] offset:528 nt
	s_add_u32 s90, s90, 0x20000
	s_addc_u32 s91, s91, 0
	global_load_dwordx4 v[222:225], v202, s[90:91] nt
	global_load_dwordx4 v[226:229], v202, s[90:91] offset:16 nt
	global_load_dwordx4 v[230:233], v202, s[90:91] offset:512 nt
	global_load_dwordx4 v[234:237], v202, s[90:91] offset:528 nt
.Lxpre_skip_b:
	v_ashrrev_i32_e32 v3, 31, v2
	v_lshl_add_u64 v[4:5], v[2:3], 2, s[4:5]
	s_mov_b64 s[8:9], 0x2b00000
	v_lshl_add_u64 v[6:7], v[4:5], 0, s[8:9]
	v_add_co_u32_e32 v4, vcc, 0x2b00000, v4
	v_mbcnt_lo_u32_b32 v1, -1, 0
	s_nop 0
	v_addc_co_u32_e32 v5, vcc, 0, v5, vcc
	flat_load_dword v3, v[4:5]
	flat_load_dword v8, v[6:7] offset:256
	flat_load_dword v9, v[6:7] offset:512
	flat_load_dword v10, v[6:7] offset:768
	v_mbcnt_hi_u32_b32 v4, -1, v1
	v_and_b32_e32 v1, 64, v4
	v_xor_b32_e32 v5, 1, v4
	v_add_u32_e32 v14, 64, v1
	v_cmp_lt_i32_e32 vcc, v5, v14
	v_xor_b32_e32 v6, 2, v4
	v_xor_b32_e32 v7, 4, v4
	v_cndmask_b32_e32 v1, v4, v5, vcc
	v_lshlrev_b32_e32 v1, 2, v1
	v_cmp_lt_i32_e32 vcc, v6, v14
	v_xor_b32_e32 v11, 8, v4
	v_xor_b32_e32 v12, 16, v4
	v_cndmask_b32_e32 v6, v4, v6, vcc
	v_lshlrev_b32_e32 v28, 2, v6
	v_cmp_lt_i32_e32 vcc, v7, v14
	v_xor_b32_e32 v13, 32, v4
	s_and_b32 s8, s2, 7
	s_lshl_b32 s8, s8, 2
	s_bfe_u32 s9, s2, 0x20003
	s_add_i32 s8, s8, s9
	s_lshl_b32 s8, s8, 8
	s_lshr_b32 s9, s2, 5
	s_lshl_b32 s9, s9, 5
	s_add_i32 s8, s8, s9
	s_add_i32 s60, s8, 32
	v_cndmask_b32_e32 v7, v4, v7, vcc
	v_lshlrev_b32_e32 v29, 2, v7
	v_cmp_lt_i32_e32 vcc, v11, v14
	s_add_i32 s8, s28, s8
	s_cmpk_lt_i32 s8, 0x2000
	s_waitcnt vmcnt(0) lgkmcnt(0)
	v_mul_f32_e32 v5, v3, v8
	ds_bpermute_b32 v5, v1, v5
	v_mul_f32_e32 v15, v9, v10
	ds_bpermute_b32 v15, v1, v15
	s_waitcnt lgkmcnt(1)
	v_fmac_f32_e32 v5, v3, v8
	ds_bpermute_b32 v3, v28, v5
	s_waitcnt lgkmcnt(1)
	v_fmac_f32_e32 v15, v9, v10
	ds_bpermute_b32 v6, v28, v15
	v_cndmask_b32_e32 v8, v4, v11, vcc
	v_lshlrev_b32_e32 v8, 2, v8
	s_waitcnt lgkmcnt(1)
	v_add_f32_e32 v3, v5, v3
	v_cmp_lt_i32_e32 vcc, v12, v14
	s_waitcnt lgkmcnt(0)
	v_add_f32_e32 v5, v15, v6
	ds_bpermute_b32 v6, v29, v3
	ds_bpermute_b32 v7, v29, v5
	s_waitcnt lgkmcnt(1)
	v_add_f32_e32 v3, v3, v6
	s_waitcnt lgkmcnt(0)
	v_add_f32_e32 v5, v5, v7
	ds_bpermute_b32 v6, v8, v3
	ds_bpermute_b32 v7, v8, v5
	v_cndmask_b32_e32 v8, v4, v12, vcc
	v_lshlrev_b32_e32 v8, 2, v8
	v_cmp_lt_i32_e32 vcc, v13, v14
	s_waitcnt lgkmcnt(1)
	v_add_f32_e32 v3, v3, v6
	s_waitcnt lgkmcnt(0)
	v_add_f32_e32 v6, v5, v7
	ds_bpermute_b32 v5, v8, v3
	ds_bpermute_b32 v7, v8, v6
	v_cndmask_b32_e32 v4, v4, v13, vcc
	v_lshlrev_b32_e32 v4, 2, v4
	s_waitcnt lgkmcnt(1)
	v_add_f32_e32 v5, v3, v5
	s_waitcnt lgkmcnt(0)
	v_add_f32_e32 v3, v6, v7
	ds_bpermute_b32 v6, v4, v5
	ds_bpermute_b32 v4, v4, v3
	s_cbranch_scc0 .LBB0_566
	v_lshlrev_b32_e32 v7, 6, v2
	v_and_b32_e32 v8, 0x1c0, v7
	v_mov_b32_e32 v9, 0
	v_lshl_add_u64 v[8:9], s[4:5], 0, v[8:9]
	s_mov_b64 s[10:11], 0x2b00400
	v_lshl_add_u64 v[18:19], v[8:9], 0, s[10:11]
	v_add_co_u32_e32 v8, vcc, 0x2b00000, v8
	flat_load_dwordx4 v[10:13], v[18:19] offset:16
	flat_load_dwordx4 v[14:17], v[18:19] offset:32
	v_addc_co_u32_e32 v9, vcc, 0, v9, vcc
	flat_load_dwordx4 v[20:23], v[8:9] offset:1024
	flat_load_dwordx4 v[24:27], v[18:19] offset:48
	s_waitcnt lgkmcnt(0)
	v_add_f32_e32 v6, v5, v6
	v_lshlrev_b32_e32 v8, 4, v2
	s_mov_b32 s11, 0x3fb8aa3b
	v_add_f32_e32 v3, v3, v4
	v_mul_f32_e32 v18, 0x3fb8aa3b, v6
	v_mul_f32_e32 v19, 0x3fb8aa3b, v3
	v_ashrrev_i32_e32 v9, 31, v8
	v_fma_f32 v30, v6, s11, -v18
	v_rndne_f32_e32 v31, v18
	v_fma_f32 v32, v3, s11, -v19
	v_rndne_f32_e32 v33, v19
	v_lshlrev_b64 v[4:5], 1, v[8:9]
	v_fmac_f32_e32 v30, 0x32a5705f, v6
	v_sub_f32_e32 v8, v18, v31
	v_fmac_f32_e32 v32, 0x32a5705f, v3
	v_sub_f32_e32 v18, v19, v33
	v_add_f32_e32 v8, v8, v30
	v_cvt_i32_f32_e32 v9, v31
	v_add_f32_e32 v18, v18, v32
	v_exp_f32_e32 v8, v8
	v_cvt_i32_f32_e32 v19, v33
	v_exp_f32_e32 v18, v18
	s_mov_b32 s37, 0xc2ce8ed0
	v_ldexp_f32 v8, v8, v9
	v_cmp_ngt_f32_e32 vcc, s37, v6
	s_mov_b32 s38, 0x42b17218
	v_ldexp_f32 v9, v18, v19
	v_cndmask_b32_e32 v8, 0, v8, vcc
	v_cmp_ngt_f32_e32 vcc, s37, v3
	v_mov_b32_e32 v7, 0x7f800000
	s_ashr_i32 s9, s8, 31
	v_cndmask_b32_e32 v9, 0, v9, vcc
	v_cmp_nlt_f32_e32 vcc, s38, v6
	s_mov_b32 s10, 8
	s_lshl_b64 s[18:19], s[8:9], 12
	v_cndmask_b32_e32 v6, v7, v8, vcc
	v_cmp_nlt_f32_e32 vcc, s38, v3
	s_add_u32 s18, s4, s18
	s_addc_u32 s19, s5, s19
	v_cndmask_b32_e32 v3, v7, v9, vcc
	s_ashr_i32 s11, s10, 31
	v_sub_f32_e32 v3, v6, v3
	s_lshl_b64 s[22:23], s[8:9], 11
	s_lshl_b64 s[20:21], s[10:11], 12
	v_add_f32_e32 v6, 0x3e4ccccd, v3
	s_mov_b32 s34, 0x3f4ccccd
	s_brev_b32 s35, 48
	s_add_u32 s22, s4, s22
	v_mov_b32_e32 v8, v6
	s_mov_b64 s[12:13], 0xb000000
	s_mov_b64 s[14:15], 0xc000000
	s_mov_b64 s[16:17], 0x8000000
	s_brev_b32 s36, 16
	v_mov_b32_e32 v2, 0x358637bd
	s_addc_u32 s23, s5, s23
	s_lshl_b64 s[30:31], s[10:11], 11
	v_mov_b32_e32 v7, v6
	v_mov_b32_e32 v3, v6
	v_xor_b32_e32 v8, 0x80000000, v8
	s_mov_b32 s9, 0xf800000
	v_mov_b32_e32 v30, 0x260
	s_mov_b32 s11, 0xe000000
	s_waitcnt vmcnt(0)
	v_pk_mul_f32 v[10:11], v[10:11], s[34:35] op_sel_hi:[1,0]
	v_pk_mul_f32 v[12:13], v[12:13], s[34:35] op_sel_hi:[1,0]
	v_pk_mul_f32 v[14:15], v[14:15], s[34:35] op_sel_hi:[1,0]
	v_pk_mul_f32 v[16:17], v[16:17], s[34:35] op_sel_hi:[1,0]
	v_pk_mul_f32 v[18:19], v[22:23], s[34:35] op_sel_hi:[1,0]
	v_pk_mul_f32 v[20:21], v[20:21], s[34:35] op_sel_hi:[1,0]
	v_pk_mul_f32 v[22:23], v[24:25], s[34:35] op_sel_hi:[1,0]
	v_pk_mul_f32 v[24:25], v[26:27], s[34:35] op_sel_hi:[1,0]
.LBB0_565:
	v_lshl_add_u64 v[26:27], s[22:23], 0, v[4:5]
	v_add_co_u32_e32 v42, vcc, 0xb000000, v26
	v_lshl_add_u64 v[32:33], s[18:19], 0, v[4:5]
	s_nop 0
	v_addc_co_u32_e32 v43, vcc, 0, v27, vcc
	v_add_co_u32_e32 v50, vcc, s35, v26
	v_lshl_add_u64 v[40:41], v[26:27], 0, s[12:13]
	v_add_co_u32_e64 v58, s[4:5], s11, v32
	v_addc_co_u32_e32 v51, vcc, 0, v27, vcc
	v_lshl_add_u64 v[48:49], v[26:27], 0, s[14:15]
	v_addc_co_u32_e64 v59, s[4:5], 0, v33, s[4:5]
	global_load_dwordx4 v[32:35], v[42:43], off nt
	global_load_dwordx4 v[36:39], v[40:41], off offset:16 nt
	s_nop 0
	global_load_dwordx4 v[40:43], v[50:51], off nt
	global_load_dwordx4 v[44:47], v[48:49], off offset:16 nt
	v_lshl_add_u64 v[56:57], v[26:27], 0, s[16:17]
	v_add_co_u32_e32 v26, vcc, s36, v26
	v_xor_b32_e32 v9, 0x80000000, v3
	s_nop 0
	v_addc_co_u32_e32 v27, vcc, 0, v27, vcc
	global_load_dwordx4 v[48:51], v[26:27], off nt
	global_load_dwordx4 v[52:55], v[56:57], off offset:16 nt
	s_add_i32 s8, s8, s10
	s_add_u32 s18, s18, s20
	s_addc_u32 s19, s19, s21
	s_add_u32 s22, s22, s30
	s_addc_u32 s23, s23, s31
	s_cmp_lt_i32 s8, s60
	s_waitcnt vmcnt(5)
	v_lshlrev_b32_e32 v26, 16, v32
	v_and_b32_e32 v27, 0xffff0000, v32
	v_lshlrev_b32_e32 v32, 16, v33
	v_and_b32_e32 v33, 0xffff0000, v33
	v_lshlrev_b32_e32 v56, 16, v34
	v_and_b32_e32 v57, 0xffff0000, v34
	v_lshlrev_b32_e32 v34, 16, v35
	v_and_b32_e32 v35, 0xffff0000, v35
	s_waitcnt vmcnt(3)
	v_lshlrev_b32_e32 v64, 16, v40
	v_and_b32_e32 v65, 0xffff0000, v40
	v_lshlrev_b32_e32 v40, 16, v41
	v_and_b32_e32 v41, 0xffff0000, v41
	v_lshlrev_b32_e32 v66, 16, v42
	v_and_b32_e32 v67, 0xffff0000, v42
	v_lshlrev_b32_e32 v42, 16, v43
	v_and_b32_e32 v43, 0xffff0000, v43
	v_lshlrev_b32_e32 v60, 16, v36
	v_and_b32_e32 v61, 0xffff0000, v36
	v_lshlrev_b32_e32 v36, 16, v37
	v_and_b32_e32 v37, 0xffff0000, v37
	v_lshlrev_b32_e32 v62, 16, v38
	v_and_b32_e32 v63, 0xffff0000, v38
	s_waitcnt vmcnt(2)
	v_lshlrev_b32_e32 v68, 16, v44
	v_and_b32_e32 v69, 0xffff0000, v44
	v_lshlrev_b32_e32 v44, 16, v45
	v_and_b32_e32 v45, 0xffff0000, v45
	v_lshlrev_b32_e32 v70, 16, v46
	v_and_b32_e32 v71, 0xffff0000, v46
	v_pk_fma_f32 v[26:27], v[6:7], v[64:65], v[26:27] neg_lo:[1,0,0] neg_hi:[1,0,0]
	v_pk_fma_f32 v[32:33], v[8:9], v[40:41], v[32:33]
	v_pk_fma_f32 v[40:41], v[6:7], v[66:67], v[56:57] neg_lo:[1,0,0] neg_hi:[1,0,0]
	v_pk_fma_f32 v[34:35], v[8:9], v[42:43], v[34:35]
	v_lshlrev_b32_e32 v38, 16, v39
	v_and_b32_e32 v39, 0xffff0000, v39
	v_lshlrev_b32_e32 v46, 16, v47
	v_and_b32_e32 v47, 0xffff0000, v47
	v_pk_fma_f32 v[36:37], v[8:9], v[44:45], v[36:37]
	v_pk_fma_f32 v[42:43], v[6:7], v[68:69], v[60:61] neg_lo:[1,0,0] neg_hi:[1,0,0]
	v_pk_fma_f32 v[44:45], v[6:7], v[70:71], v[62:63] neg_lo:[1,0,0] neg_hi:[1,0,0]
	v_pk_mul_f32 v[64:65], v[32:33], v[32:33]
	v_pk_mul_f32 v[66:67], v[26:27], v[26:27]
	v_pk_mul_f32 v[68:69], v[34:35], v[34:35]
	v_pk_mul_f32 v[70:71], v[40:41], v[40:41]
	v_pk_fma_f32 v[38:39], v[8:9], v[46:47], v[38:39]
	v_pk_mov_b32 v[76:77], v[66:67], v[64:65] op_sel:[1,0]
	v_mov_b32_e32 v67, v65
	v_pk_mov_b32 v[64:65], v[70:71], v[68:69] op_sel:[1,0]
	v_mov_b32_e32 v71, v69
	v_mul_f32_e32 v75, v38, v38
	v_mul_f32_e32 v72, v43, v43
	v_mul_f32_e32 v74, v37, v37
	v_pk_add_f32 v[66:67], v[76:77], v[66:67]
	v_pk_add_f32 v[64:65], v[64:65], v[70:71]
	v_mul_f32_e32 v9, v44, v44
	v_mul_f32_e32 v31, v45, v45
	v_mul_f32_e32 v78, v39, v39
	v_pk_fma_f32 v[68:69], v[42:43], v[42:43], v[72:73] op_sel_hi:[1,1,0]
	v_pk_fma_f32 v[72:73], v[36:37], v[36:37], v[74:75] op_sel_hi:[1,1,0]
	v_pk_add_f32 v[66:67], v[66:67], v[66:67] op_sel:[0,1] op_sel_hi:[1,0]
	v_pk_add_f32 v[64:65], v[64:65], v[64:65] op_sel:[0,1] op_sel_hi:[1,0]
	v_mov_b32_e32 v69, v75
	v_mov_b32_e32 v73, v78
	v_mov_b32_e32 v67, v9
	v_mov_b32_e32 v65, v31
	v_pk_add_f32 v[68:69], v[68:69], v[72:73]
	v_pk_add_f32 v[64:65], v[66:67], v[64:65]
	s_waitcnt vmcnt(1)
	v_lshlrev_b32_e32 v46, 16, v48
	v_pk_add_f32 v[64:65], v[64:65], v[68:69]
	v_and_b32_e32 v47, 0xffff0000, v48
	v_add_f32_e32 v9, v64, v65
	ds_bpermute_b32 v31, v1, v9
	v_lshlrev_b32_e32 v56, 16, v50
	v_and_b32_e32 v57, 0xffff0000, v50
	v_lshlrev_b32_e32 v50, 16, v51
	v_and_b32_e32 v51, 0xffff0000, v51
	s_waitcnt lgkmcnt(0)
	v_add_f32_e32 v9, v9, v31
	ds_bpermute_b32 v31, v28, v9
	v_lshlrev_b32_e32 v48, 16, v49
	v_and_b32_e32 v49, 0xffff0000, v49
	s_waitcnt vmcnt(0)
	v_lshlrev_b32_e32 v60, 16, v52
	v_and_b32_e32 v61, 0xffff0000, v52
	s_waitcnt lgkmcnt(0)
	v_add_f32_e32 v9, v9, v31
	ds_bpermute_b32 v31, v29, v9
	v_lshlrev_b32_e32 v52, 16, v53
	v_and_b32_e32 v53, 0xffff0000, v53
	v_lshlrev_b32_e32 v62, 16, v54
	v_and_b32_e32 v63, 0xffff0000, v54
	s_waitcnt lgkmcnt(0)
	v_add_f32_e32 v9, v9, v31
	v_fmamk_f32 v9, v9, 0x3c000000, v2
	v_mul_f32_e32 v31, 0x4f800000, v9
	v_cmp_gt_f32_e32 vcc, s9, v9
	v_lshlrev_b32_e32 v54, 16, v55
	v_and_b32_e32 v55, 0xffff0000, v55
	v_cndmask_b32_e32 v9, v9, v31, vcc
	v_sqrt_f32_e32 v31, v9
	s_nop 0
	v_add_u32_e32 v64, -1, v31
	v_add_u32_e32 v65, 1, v31
	v_fma_f32 v66, -v64, v31, v9
	v_fma_f32 v67, -v65, v31, v9
	v_cmp_ge_f32_e64 s[4:5], 0, v66
	s_nop 1
	v_cndmask_b32_e64 v31, v31, v64, s[4:5]
	v_cmp_lt_f32_e64 s[4:5], 0, v67
	s_nop 1
	v_cndmask_b32_e64 v31, v31, v65, s[4:5]
	v_mul_f32_e32 v64, 0x37800000, v31
	v_cndmask_b32_e32 v31, v31, v64, vcc
	v_cmp_class_f32_e32 vcc, v9, v30
	s_nop 1
	v_cndmask_b32_e32 v9, v31, v9, vcc
	v_div_scale_f32 v31, s[4:5], v9, v9, 1.0
	v_rcp_f32_e32 v65, v31
	v_div_scale_f32 v64, vcc, 1.0, v9, 1.0
	v_fma_f32 v66, -v31, v65, 1.0
	v_fmac_f32_e32 v65, v66, v65
	v_mul_f32_e32 v66, v64, v65
	v_fma_f32 v67, -v31, v66, v64
	v_fmac_f32_e32 v66, v67, v65
	v_fma_f32 v31, -v31, v66, v64
	v_div_fmas_f32 v31, v31, v65, v66
	v_div_fixup_f32 v64, v31, v9, 1.0
	v_pk_mul_f32 v[26:27], v[26:27], v[64:65] op_sel_hi:[1,0]
	v_pk_mul_f32 v[34:35], v[34:35], v[64:65] op_sel_hi:[1,0]
	v_pk_mul_f32 v[40:41], v[40:41], v[64:65] op_sel_hi:[1,0]
	v_pk_mul_f32 v[32:33], v[32:33], v[64:65] op_sel_hi:[1,0]
	v_pk_mul_f32 v[26:27], v[20:21], v[26:27]
	v_pk_mul_f32 v[40:41], v[10:11], v[40:41]
	v_pk_mul_f32 v[34:35], v[12:13], v[34:35]
	v_pk_mul_f32 v[36:37], v[36:37], v[64:65] op_sel_hi:[1,0]
	v_pk_mul_f32 v[42:43], v[42:43], v[64:65] op_sel_hi:[1,0]
	v_pk_mul_f32 v[38:39], v[38:39], v[64:65] op_sel_hi:[1,0]
	v_pk_mul_f32 v[44:45], v[44:45], v[64:65] op_sel_hi:[1,0]
	v_pk_mul_f32 v[32:33], v[18:19], v[32:33]
	v_pk_mul_f32 v[26:27], v[26:27], v[46:47]
	v_pk_mul_f32 v[46:47], v[34:35], v[50:51]
	v_pk_mul_f32 v[34:35], v[40:41], v[56:57]
	v_pk_mul_f32 v[42:43], v[14:15], v[42:43]
	v_pk_mul_f32 v[36:37], v[16:17], v[36:37]
	v_pk_mul_f32 v[44:45], v[22:23], v[44:45]
	v_pk_mul_f32 v[38:39], v[24:25], v[38:39]
	v_pk_mul_f32 v[48:49], v[32:33], v[48:49]
	v_cvt_pk_bf16_f32 v32, v26, v27
	v_pk_mul_f32 v[36:37], v[36:37], v[52:53]
	v_cvt_pk_bf16_f32 v33, v48, v49
	v_cvt_pk_bf16_f32 v34, v34, v35
	v_cvt_pk_bf16_f32 v35, v46, v47
	v_pk_mul_f32 v[40:41], v[42:43], v[60:61]
	v_pk_mul_f32 v[38:39], v[38:39], v[54:55]
	v_pk_mul_f32 v[42:43], v[44:45], v[62:63]
	global_store_dwordx4 v[58:59], v[32:35], off
	s_nop 1
	v_cvt_pk_bf16_f32 v32, v40, v41
	v_cvt_pk_bf16_f32 v33, v36, v37
	v_cvt_pk_bf16_f32 v34, v42, v43
	v_cvt_pk_bf16_f32 v35, v38, v39
	global_store_dwordx4 v[58:59], v[32:35], off offset:16
	s_cbranch_scc1 .LBB0_565
.LBB0_566:
	s_cmp_gt_i32 s27, 5
	s_cselect_b64 s[4:5], -1, 0
	s_and_b64 s[6:7], s[6:7], s[4:5]
	s_andn2_b64 vcc, exec, s[6:7]
	s_cbranch_vccnz .LBB0_616
	s_waitcnt vmcnt(0)
	v_cmp_eq_u32_e32 vcc, 0, v0
	s_waitcnt vmcnt(0) lgkmcnt(0)
	s_barrier
	s_and_saveexec_b64 s[6:7], vcc
	s_cbranch_execz .LBB0_615
	s_and_b32 s8, s2, 7
	s_lshl_b32 s8, s8, 2
	s_bfe_u32 s9, s2, 0x20003
	s_add_i32 s8, s8, s9
	s_lshl_b32 s8, s8, 6
	s_add_i32 s8, s8, 0x6400
	v_mov_b32_e32 v1, s8
	s_mul_i32 s9, s33, s33
	s_lshl_b32 s9, s9, 16
	s_lshl_b32 s10, s33, 8
	s_or_b32 s9, s9, s10
	s_or_b32 s9, s9, 1
	v_mov_b32_e32 v2, s9
	global_atomic_add v1, v2, s[24:25]
	v_mov_b32_e32 v3, 0x7600
	s_mov_b32 s14, 0
.Lpb_spin:
	global_load_dword v4, v1, s[24:25] sc1
	global_load_dword v5, v3, s[24:25] sc1
	s_waitcnt vmcnt(0)
	v_readfirstlane_b32 s10, v4
	v_readfirstlane_b32 s11, v5
	s_nop 3
	s_and_b32 s12, s10, 0xff
	s_cmp_ge_u32 s12, 8
	s_cselect_b32 s12, 1, 0
	s_cmp_ge_u32 s11, 8
	s_cselect_b32 s13, 1, 0
	s_and_b32 s12, s12, s13
	s_cmp_lg_u32 s12, 0
	s_cbranch_scc1 .Lpb_done
	s_sleep 1
	s_add_i32 s14, s14, 1
	s_cmp_lt_u32 s14, 0x40000
	s_cbranch_scc1 .Lpb_spin
.Lpb_done:
	s_bfe_u32 s11, s10, 0x80008
	s_lshr_b32 s12, s10, 16
	s_lshl_b32 s12, s12, 3
	s_mul_i32 s11, s11, s11
	s_cmp_eq_u32 s11, s12
	s_cbranch_scc1 .LBB0_615
	buffer_wbl2 sc1
	s_waitcnt vmcnt(0)
	v_add_u32_e32 v1, 4, v1
	v_mov_b32_e32 v2, 1
	global_atomic_add v1, v2, s[24:25]
	s_mov_b32 s14, 0
.Lpb_spin2:
	global_load_dword v4, v1, s[24:25] sc1
	s_waitcnt vmcnt(0)
	v_readfirstlane_b32 s10, v4
	s_nop 3
	s_cmp_ge_u32 s10, 8
	s_cbranch_scc1 .Lpb_done2
	s_sleep 1
	s_add_i32 s14, s14, 1
	s_cmp_lt_u32 s14, 0x40000
	s_cbranch_scc1 .Lpb_spin2
.Lpb_done2:
	buffer_inv sc1
	s_waitcnt vmcnt(0)

.LBB0_616:
	s_cmp_lt_i32 s26, 6
	s_cselect_b64 s[6:7], -1, 0
	s_and_b64 s[4:5], s[6:7], s[4:5]
	s_andn2_b64 vcc, exec, s[4:5]
	s_cbranch_vccnz .LBB0_664
	s_cmpk_gt_i32 s2, 0xff
	v_readfirstlane_b32 s33, v0
	s_cbranch_scc1 .LBB0_664
	s_and_b32 s80, s2, 7
	s_lshl_b32 s80, s80, 2
	s_bfe_u32 s81, s2, 0x20003
	s_add_i32 s80, s80, s81
	s_lshr_b32 s80, s80, 4
	s_mul_i32 s80, s80, 0x6000
	s_lshr_b32 s81, s2, 5
	s_lshl_b32 s81, s81, 10
	s_add_u32 s80, s80, s81
	s_lshr_b32 s81, s33, 6
	s_and_b32 s81, s81, 3
	s_lshl_b32 s81, s81, 7
	s_add_u32 s80, s80, s81
	s_add_u32 s80, s80, 0x2904000
	s_add_u32 s92, s24, s80
	s_addc_u32 s93, s25, 0
	v_bfe_u32 v205, v0, 4, 2
	v_lshlrev_b32_e32 v205, 5, v205
	global_load_dwordx4 v[146:149], v205, s[92:93] sc1
	global_load_dwordx4 v[242:245], v205, s[92:93] offset:16 sc1
	global_load_dwordx4 v[246:249], v205, s[92:93] offset:512 sc1
	global_load_dwordx4 v[250:253], v205, s[92:93] offset:528 sc1
	v_lshrrev_b32_e32 v150, 1, v0
	s_waitcnt lgkmcnt(0)
	v_lshrrev_b32_e32 v4, 5, v0
	v_lshlrev_b32_e32 v1, 4, v0
	v_and_b32_e32 v2, 32, v0
	v_and_b32_e32 v3, 24, v150
	v_and_b32_e32 v4, 4, v4
	v_bfe_u32 v5, v0, 2, 2
	s_add_u32 s37, s24, 0xe000000
	v_bfe_u32 v12, v0, 2, 4
	v_bitop3_b32 v10, v1, v2, 48 bitop3:0x6c
	v_and_b32_e32 v11, 64, v0
	v_or3_b32 v3, v4, v5, v3
	v_lshrrev_b32_e32 v4, 3, v0
	v_or_b32_e32 v13, 0x2000, v1
	s_addc_u32 s38, s25, 0
	v_or_b32_e32 v2, v10, v11
	v_and_or_b32 v5, v4, 48, v12
	v_and_or_b32 v4, v4, 32, v3
	v_lshrrev_b32_e32 v1, 7, v13
	s_movk_i32 s4, 0x70
	s_add_u32 s39, s24, 0x1e00000
	v_lshl_or_b32 v132, v4, 12, v2
	v_and_or_b32 v4, v1, s4, v12
	s_movk_i32 s4, 0x60
	s_addc_u32 s40, s25, 0
	s_ashr_i32 s42, s2, 31
	v_and_or_b32 v1, v1, s4, v3
	s_lshr_b32 s4, s42, 29
	s_add_i32 s4, s2, s4
	s_ashr_i32 s5, s4, 3
	s_and_b32 s4, s4, -8
	s_lshr_b32 s11, s33, 6
	s_sub_i32 s4, s2, s4
	s_lshr_b32 s36, s33, 8
	s_lshl_b32 s41, s11, 10
	s_lshl_b32 s7, s4, 5
	s_mul_i32 s6, s4, 33
	s_cmp_lt_i32 s4, 0
	s_cselect_b32 s4, s6, s7
	s_add_i32 s4, s4, s5
	s_ashr_i32 s5, s4, 31
	s_lshr_b32 s5, s5, 27
	s_add_i32 s5, s4, s5
	s_ashr_i32 s6, s5, 5
	s_and_b32 s5, s5, 0xffe0
	s_sub_i32 s5, s4, s5
	s_bfe_i32 s4, s5, 0x80000
	s_bfe_u32 s4, s4, 0x2000d
	s_add_i32 s7, s5, s4
	s_bfe_i32 s4, s7, 0x80000
	s_and_b32 s7, s7, 0xfc
	s_sub_i32 s5, s5, s7
	s_lshl_b32 s6, s6, 2
	s_sext_i32_i16 s4, s4
	s_sext_i32_i8 s5, s5
	s_lshr_b32 s4, s4, 2
	s_add_i32 s8, s6, s5
	s_ashr_i32 s9, s8, 31
	s_bfe_i64 s[12:13], s[4:5], 0x100000
	s_lshl_b64 s[6:7], s[8:9], 20
	s_lshl_b64 s[12:13], s[12:13], 20
	s_add_u32 s28, s39, s12
	s_addc_u32 s29, s40, s13
	s_add_i32 s43, s41, 0
	s_add_i32 m0, s43, 0x10000
	v_lshl_or_b32 v136, v1, 12, v2
	global_load_lds_dwordx4 v132, s[28:29]
	s_add_i32 m0, s43, 0x12000
	s_add_u32 s12, s28, 0x80000
	global_load_lds_dwordx4 v136, s[28:29]
	s_addc_u32 s13, s29, 0
	s_add_i32 m0, s43, 0x14000
	v_lshl_or_b32 v130, v5, 12, v2
	global_load_lds_dwordx4 v132, s[12:13]
	s_add_i32 m0, s43, 0x16000
	v_lshl_or_b32 v134, v4, 12, v2
	global_load_lds_dwordx4 v136, s[12:13]
	s_add_u32 s12, s37, s6
	s_addc_u32 s13, s38, s7
	s_add_i32 s44, s43, 0x2000
	s_mov_b32 m0, s43
	s_add_u32 s6, s12, 0x80000
	global_load_lds_dwordx4 v130, s[12:13]
	s_mov_b32 m0, s44
	s_addc_u32 s7, s13, 0
	s_add_i32 s45, s43, 0x4000
	global_load_lds_dwordx4 v134, s[12:13]
	s_mov_b32 m0, s45
	s_add_i32 s46, s43, 0x6000
	global_load_lds_dwordx4 v130, s[6:7]
	s_mov_b32 m0, s46
	v_mov_b32_e32 v133, 0
	global_load_lds_dwordx4 v134, s[6:7]
	v_mov_b32_e32 v137, v133
	v_mov_b32_e32 v131, v133
	v_mov_b32_e32 v135, v133
	v_lshl_add_u64 v[8:9], s[28:29], 0, v[132:133]
	v_lshl_add_u64 v[6:7], s[28:29], 0, v[136:137]
	v_lshl_add_u64 v[4:5], s[12:13], 0, v[130:131]
	s_cmp_lg_u32 s36, 1
	v_lshl_add_u64 v[2:3], s[12:13], 0, v[134:135]
	s_cbranch_scc1 .LBB0_620
	s_barrier

.LBB0_635:
	s_lshl_b32 s0, s9, 5
	s_lshl_b32 s1, s10, 8
	s_or_b32 s0, s1, s0
	v_and_or_b32 v130, v150, 24, s0
	s_ashr_i32 s0, s8, 31
	s_lshr_b32 s0, s0, 28
	s_add_i32 s0, s8, s0
	s_ashr_i32 s0, s0, 4
	s_mul_hi_i32 s1, s0, 0x6000
	s_mulk_i32 s0, 0x6000
	s_add_u32 s0, s24, s0
	v_ashrrev_i32_e32 v131, 31, v130
	s_addc_u32 s1, s25, s1
	v_lshlrev_b64 v[194:195], 2, v[130:131]
	s_lshl_b32 s4, s8, 8
	v_lshl_add_u64 v[130:131], s[0:1], 0, v[194:195]
	s_mov_b32 s2, 0x2904000
	v_add_u32_e32 v196, s4, v204
	v_add_co_u32_e32 v132, vcc, s2, v130
	v_ashrrev_i32_e32 v197, 31, v196
	s_nop 0
	v_addc_co_u32_e32 v133, vcc, 0, v131, vcc
	v_lshl_add_u64 v[202:203], s[14:15], 0, v[194:195]
	v_lshlrev_b64 v[198:199], 13, v[196:197]
	s_barrier
	flat_load_dwordx4 v[134:137], v[132:133] sc1
	v_lshl_add_u64 v[132:133], v[202:203], 0, v[198:199]
	s_mov_b64 s[0:1], 0x2904000
	v_lshl_add_u64 v[130:131], v[130:131], 0, s[0:1]
	flat_load_dwordx4 v[142:145], v[130:131] offset:16 sc1
	flat_load_dwordx4 v[138:141], v[130:131] offset:512 sc1
	s_nop 0
	flat_load_dwordx4 v[130:133], v[130:131] offset:528 sc1
	v_or_b32_e32 v146, 16, v196
	v_ashrrev_i32_e32 v147, 31, v146
	v_lshlrev_b64 v[146:147], 13, v[146:147]
	v_lshl_add_u64 v[146:147], v[202:203], 0, v[146:147]
	v_or_b32_e32 v146, 32, v196
	v_ashrrev_i32_e32 v147, 31, v146
	v_lshlrev_b64 v[146:147], 13, v[146:147]
	v_lshl_add_u64 v[146:147], v[202:203], 0, v[146:147]
	v_or_b32_e32 v146, 48, v196
	v_ashrrev_i32_e32 v147, 31, v146
	v_lshlrev_b64 v[146:147], 13, v[146:147]
	v_lshl_add_u64 v[150:151], v[202:203], 0, v[146:147]
	s_nop 0
	v_mbcnt_lo_u32_b32 v200, -1, 0
	v_mbcnt_hi_u32_b32 v200, -1, v200
	v_and_b32_e32 v205, 64, v200
	v_xor_b32_e32 v201, 16, v200
	v_add_u32_e32 v222, 64, v205
	v_cmp_lt_i32_e32 vcc, v201, v222
	v_and_b32_e32 v197, 63, v0
	s_lshl_b32 s0, s9, 2
	v_cndmask_b32_e32 v201, v200, v201, vcc
	v_lshlrev_b32_e32 v205, 2, v201
	v_lshlrev_b32_e32 v1, 4, v1
	s_add_i32 s2, s0, 0
	s_waitcnt vmcnt(0) lgkmcnt(0)
	s_mov_b32 s62, 0x0da24260
	s_mov_b32 s63, 0x7fffffff
	v_max_f32_e64 v254, |v130|, s62
	v_bfi_b32 v130, s63, v254, v130
	v_max_f32_e64 v254, |v131|, s62
	v_bfi_b32 v131, s63, v254, v131
	v_max_f32_e64 v254, |v132|, s62
	v_bfi_b32 v132, s63, v254, v132
	v_max_f32_e64 v254, |v133|, s62
	v_bfi_b32 v133, s63, v254, v133
	v_max_f32_e64 v254, |v134|, s62
	v_bfi_b32 v134, s63, v254, v134
	v_max_f32_e64 v254, |v135|, s62
	v_bfi_b32 v135, s63, v254, v135
	v_max_f32_e64 v254, |v136|, s62
	v_bfi_b32 v136, s63, v254, v136
	v_max_f32_e64 v254, |v137|, s62
	v_bfi_b32 v137, s63, v254, v137
	v_max_f32_e64 v254, |v138|, s62
	v_bfi_b32 v138, s63, v254, v138
	v_max_f32_e64 v254, |v139|, s62
	v_bfi_b32 v139, s63, v254, v139
	v_max_f32_e64 v254, |v140|, s62
	v_bfi_b32 v140, s63, v254, v140
	v_max_f32_e64 v254, |v141|, s62
	v_bfi_b32 v141, s63, v254, v141
	v_max_f32_e64 v254, |v142|, s62
	v_bfi_b32 v142, s63, v254, v142
	v_max_f32_e64 v254, |v143|, s62
	v_bfi_b32 v143, s63, v254, v143
	v_max_f32_e64 v254, |v144|, s62
	v_bfi_b32 v144, s63, v254, v144
	v_max_f32_e64 v254, |v145|, s62
	v_bfi_b32 v145, s63, v254, v145
	v_pk_mul_f32 v[124:125], v[124:125], v[144:145]
	v_pk_mul_f32 v[128:129], v[128:129], v[136:137]
	v_pk_mul_f32 v[126:127], v[126:127], v[134:135]
	v_pk_mul_f32 v[122:123], v[122:123], v[142:143]
	v_mul_f32_e32 v201, v127, v127
	v_mul_f32_e32 v206, v129, v129
	v_mul_f32_e32 v207, v123, v123
	v_mul_f32_e32 v208, v125, v125
	v_pk_mul_f32 v[120:121], v[120:121], v[140:141]
	v_pk_mul_f32 v[118:119], v[118:119], v[138:139]
	v_fmac_f32_e32 v201, v126, v126
	v_fmac_f32_e32 v206, v128, v128
	v_fmac_f32_e32 v207, v122, v122
	v_fmac_f32_e32 v208, v124, v124
	v_pk_mul_f32 v[116:117], v[116:117], v[132:133]
	v_pk_mul_f32 v[114:115], v[114:115], v[130:131]
	v_mul_f32_e32 v209, v119, v119
	v_mul_f32_e32 v210, v121, v121
	v_add_f32_e32 v201, v201, v206
	v_add_f32_e32 v206, v207, v208
	v_mul_f32_e32 v211, v115, v115
	v_fmac_f32_e32 v209, v118, v118
	v_fmac_f32_e32 v210, v120, v120
	v_add_f32_e32 v201, v201, v206
	v_mul_f32_e32 v206, v117, v117
	v_add_f32_e32 v207, v209, v210
	v_fmac_f32_e32 v211, v114, v114
	v_fmac_f32_e32 v206, v116, v116
	v_add_f32_e32 v201, v201, v207
	v_add_f32_e32 v206, v211, v206
	v_add_f32_e32 v201, v201, v206
	ds_bpermute_b32 v207, v205, v201
	v_xor_b32_e32 v206, 32, v200
	v_cmp_lt_i32_e32 vcc, v206, v222
	s_nop 1
	v_cndmask_b32_e32 v200, v200, v206, vcc
	v_lshlrev_b32_e32 v206, 2, v200
	s_waitcnt lgkmcnt(0)
	v_add_f32_e32 v200, v201, v207
	ds_bpermute_b32 v201, v206, v200
	v_cmp_gt_u32_e32 vcc, 16, v197
	s_and_saveexec_b64 s[0:1], vcc
	s_cbranch_execz .LBB0_637
	s_lshl_b32 s3, s36, 10
	s_add_i32 s3, s2, s3
	v_add_u32_e32 v207, s3, v1
	s_waitcnt lgkmcnt(0)
	v_add_f32_e32 v200, v200, v201
	ds_write_b32 v207, v200
